# GEMM w_in/mlp_in: start skew for workgroups that have one tile fewer, so epilogue store bursts of different groups no longer coincide
# speedup vs baseline: 1.0168x; 1.0168x over previous
;     __device__ __forceinline__ bool next(int i, Unit& u) const {
;         const long L = (long)i * G + c; if (L >= nwg + nsplit * nN * KSPLIT) return false;
;         int pm, pn, ks;
;         if (L >= nwg) { const int e = (int)L - nwg, cu = e / KSPLIT; ks = e % KSPLIT; pm = nM + cu / nN; pn = cu % nN; }
;         else {
;             int wgid = (int)L; { const int q = nwg / NXCD, r = nwg % NXCD, xcd = wgid % NXCD, off = wgid / NXCD; wgid = (xcd < r ? xcd * (q + 1) : r * (q + 1) + (xcd - r) * q) + off; }
;             const int nig = WGM * nN, gid = wgid / nig, fm = gid * WGM, gsz = (nM - fm) < WGM ? (nM - fm) : WGM;
;             pm = fm + ((wgid % nig) % gsz); pn = (wgid % nig) / gsz; ks = -1;
;         }
;         u.pm = pm; u.pn = pn; u.ks = ks; return true;
; template <class EpiT, bool ALIGN_EPI>
; __device__ __forceinline__ void gemm_phase(LAS unsigned char* lds, const Gemm g, const StaticOrder& S, const EpiT& E, const int tid) {
;     const int wid = __builtin_amdgcn_readfirstlane(tid >> 6), lane = tid & 63, wr = wid >> 2, wc = wid & 3, fr = lane & 15, fq = lane >> 4;
;     const int K = g.K;
;     unsigned voffA[2], voffB[2];
; #pragma unroll
;     for (int i = 0; i < 2; ++i) { int R, C; stage_rc(tid * 16 + i * 8192, R, C); const int Rb = (R & ~31) + perm32(R & 31);
;         voffA[i] = (unsigned)(R * K + C) * 2u; voffB[i] = (unsigned)(Rb * K + C) * 2u; }
;     const size_t kstep = (size_t)(BK * 2);
;     const size_t hstep = (size_t)HALF * K * 2;
;     const size_t tstep = 2 * hstep;
;     const unsigned ldsw = (unsigned)wid * 1024u;
;     const int aoff = lds_byte(wr * 64 + fr, fq * 8), boff = lds_byte(wc * 32 + fr, fq * 8);
;     ...
;     Unit cur, nxt; int ui = 0;
;     if (!S.next(0, cur)) return;
;     f32x4 acc[2][2][4][2];
; #pragma unroll
;     for (int a = 0; a < 2; ++a)
; #pragma unroll
;         for (int b = 0; b < 2; ++b)
; #pragma unroll
;             for (int m = 0; m < 4; ++m)
; #pragma unroll
;                 for (int n = 0; n < 2; ++n) acc[a][b][m][n] = (f32x4){0.f, 0.f, 0.f, 0.f};
;     bf16x8 At[4][2], B0[2][2], B1[2][2];
;     const char* cA; const char* cB; PG8_PTRS(cur, cA, cB);
;     PG8_STAGE(PG8_SB(0, 0), cB, voffB); PG8_STAGE(PG8_SB(0, 1), cB + hstep, voffB); PG8_STAGE(PG8_SA(0, 0), cA, voffA); PG8_STAGE(PG8_SA(0, 1), cA + hstep, voffA);
;     if (wr == 1) PG8_BAR;
;     PG8_WAIT_V(2); PG8_BAR;
.LBB0_171:
	s_and_b64 vcc, exec, s[0:1]
	s_cbranch_vccz .LBB0_190
	s_lshl_b32 s30, s97, 4
	s_cmp_ge_i32 s2, s30
	v_readfirstlane_b32 s1, v166
	s_cbranch_scc1 .LBB0_190
	s_cmp_eq_u32 s97, 0x88
	s_cbranch_scc0 .Lskew_done_mi
	s_bitcmp1_b32 s2, 7
	s_cbranch_scc0 .Lskew_done_mi
	s_mov_b32 s32, 4
.Lskew_loop_mi:
	s_sleep 127
	s_add_i32 s32, s32, -1
	s_cmp_lg_u32 s32, 0
	s_cbranch_scc1 .Lskew_loop_mi
.Lskew_done_mi:
	s_waitcnt vmcnt(0)
	v_lshlrev_b32_e32 v0, 4, v166
	v_add_u32_e32 v1, 0x2000, v0
	v_ashrrev_i32_e32 v2, 31, v1
	v_lshrrev_b32_e32 v2, 22, v2
	v_add_u32_e32 v2, v1, v2
	v_ashrrev_i32_e32 v8, 10, v2
	v_mul_i32_i24_e32 v2, 0x400, v8
	v_sub_u32_e32 v1, v1, v2
	v_lshrrev_b32_e32 v2, 4, v1
	v_readlane_b32 s4, v255, 17
	v_bitop3_b32 v1, v2, v1, 32 bitop3:0x6c
	v_readlane_b32 s5, v255, 18
	v_ashrrev_i32_e32 v2, 31, v1
	s_ashr_i32 s5, s4, 31
	s_mov_b32 s0, s4
	v_lshrrev_b32_e32 v2, 26, v2
	v_writelane_b32 v255, s0, 17
	s_lshl_b64 s[4:5], s[4:5], 23
	v_add_u32_e32 v2, v1, v2
	v_lshlrev_b32_e32 v3, 3, v8
	v_writelane_b32 v255, s1, 18
	s_add_u32 s0, s73, s4
	v_ashrrev_i32_e32 v9, 6, v2
	v_and_b32_e32 v3, -16, v3
	s_addc_u32 s4, s57, s5
	v_add_u32_e32 v3, v9, v3
	s_add_u32 s24, s0, 0x2400000
	v_and_b32_e32 v4, 3, v9
	s_mov_b32 s0, 0x1fffe0
	v_lshrrev_b32_e32 v5, 2, v3
	v_lshlrev_b32_e32 v6, 1, v3
	v_and_b32_e32 v2, 0xc0, v2
	v_and_or_b32 v4, v3, s0, v4
	v_and_b32_e32 v5, 4, v5
	v_and_b32_e32 v6, 24, v6
	v_sub_u32_e32 v1, v1, v2
	v_or3_b32 v4, v4, v5, v6
	v_lshlrev_b32_e32 v5, 5, v8
	v_ashrrev_i16_sdwa v1, v252, sext(v1) dst_sel:DWORD dst_unused:UNUSED_PAD src0_sel:DWORD src1_sel:BYTE_0
	v_and_b32_e32 v5, 32, v5
	v_bfe_i32 v10, v1, 0, 16
	v_add_lshl_u32 v1, v5, v10, 1
	v_lshl_add_u32 v128, v4, 11, v1
	v_lshl_add_u32 v130, v3, 11, v1
	v_bfe_i32 v1, v166, 27, 1
	v_lshrrev_b32_e32 v1, 22, v1
	v_add_u32_e32 v1, v0, v1
	v_and_b32_e32 v1, 0xfffffc00, v1
	v_sub_u32_e32 v0, v0, v1
	v_lshrrev_b32_e32 v1, 4, v0
	v_ashrrev_i32_e32 v2, 31, v166
	v_bitop3_b32 v0, v1, v0, 32 bitop3:0x6c
	v_lshrrev_b32_e32 v2, 26, v2
	v_ashrrev_i32_e32 v1, 31, v0
	v_add_u32_e32 v2, v166, v2
	v_lshrrev_b32_e32 v1, 26, v1
	v_ashrrev_i32_e32 v12, 6, v2
	v_add_u32_e32 v1, v0, v1
	v_lshlrev_b32_e32 v2, 3, v12
	v_ashrrev_i32_e32 v11, 6, v1
	v_and_b32_e32 v2, -16, v2
	v_add_u32_e32 v2, v11, v2
	v_and_b32_e32 v3, 3, v11
	v_lshrrev_b32_e32 v4, 2, v2
	v_lshlrev_b32_e32 v5, 1, v2
	v_and_b32_e32 v1, 0xc0, v1
	v_and_or_b32 v3, v2, s0, v3
	v_and_b32_e32 v4, 4, v4
	v_and_b32_e32 v5, 24, v5
	v_sub_u32_e32 v0, v0, v1
	v_or3_b32 v3, v3, v4, v5
	v_lshlrev_b32_e32 v4, 5, v12
	v_ashrrev_i16_sdwa v0, v252, sext(v0) dst_sel:DWORD dst_unused:UNUSED_PAD src0_sel:DWORD src1_sel:BYTE_0
	v_and_b32_e32 v4, 32, v4
	v_bfe_i32 v13, v0, 0, 16
	v_add_lshl_u32 v0, v4, v13, 1
	v_readlane_b32 s6, v253, 57
	v_lshl_add_u32 v156, v3, 11, v0
	v_lshl_add_u32 v132, v2, 11, v0
	v_mov_b32_e32 v0, s6
	v_alignbit_b32 v0, s97, v0, 31
	s_addc_u32 s25, s4, 0
	v_readfirstlane_b32 s0, v0
	s_mul_i32 s0, s0, s6
	v_readlane_b32 s6, v253, 58
	s_add_i32 s0, s0, s6
	s_ashr_i32 s6, s0, 31
	s_lshr_b32 s6, s6, 25
	s_add_i32 s6, s0, s6
	s_ashr_i32 s7, s6, 7
	s_lshl_b32 s8, s7, 3
	s_sub_i32 s7, s97, s8
	s_min_i32 s9, s7, 8
	s_sext_i32_i8 s7, s9
	v_cvt_f32_i32_e32 v0, s7
	s_and_b32 s6, s6, 0xffffff80
	s_sub_i32 s10, s0, s6
	v_cvt_f32_i32_e32 v1, s10
	v_rcp_iflag_f32_e32 v2, v0
	s_xor_b32 s0, s10, s7
	s_ashr_i32 s4, s1, 6
	s_ashr_i32 s0, s0, 30
	v_mul_f32_e32 v2, v1, v2
	v_trunc_f32_e32 v2, v2
	v_fma_f32 v1, -v2, v0, v1
	v_cvt_i32_f32_e32 v2, v2
	s_ashr_i32 s5, s1, 8
	s_lshl_b32 s33, s4, 10
	s_or_b32 s0, s0, 1
	v_cmp_ge_f32_e64 s[6:7], |v1|, |v0|
	s_and_b64 s[6:7], s[6:7], exec
	s_cselect_b32 s0, s0, 0
	v_readfirstlane_b32 s6, v2
	s_add_i32 s0, s6, s0
	s_mul_i32 s6, s0, s9
	s_sub_i32 s6, s10, s6
	s_sext_i32_i8 s6, s6
	s_add_i32 s20, s8, s6
	s_ashr_i32 s21, s20, 31
	s_lshl_b64 s[6:7], s[20:21], 19
	s_add_u32 s22, s94, s6
	s_addc_u32 s23, s95, s7
	s_bfe_i64 s[6:7], s[0:1], 0x80000
	s_lshl_b64 s[6:7], s[6:7], 19
	s_add_u32 s26, s24, s6
	s_addc_u32 s27, s25, s7
	s_add_i32 s21, s33, 0
	s_add_i32 m0, s21, 0x10000
	v_mov_b32_e32 v129, v157
	global_load_lds_dwordx4 v156, s[26:27]
	s_add_i32 m0, s21, 0x12000
	s_add_u32 s6, s26, 0x40000
	global_load_lds_dwordx4 v128, s[26:27]
	s_addc_u32 s7, s27, 0
	s_add_i32 m0, s21, 0x14000
	s_add_i32 s53, s21, 0x2000
	global_load_lds_dwordx4 v156, s[6:7]
	s_add_i32 m0, s21, 0x16000
	v_mov_b32_e32 v133, v157
	global_load_lds_dwordx4 v128, s[6:7]
	s_mov_b32 m0, s21
	s_add_u32 s6, s22, 0x40000
	global_load_lds_dwordx4 v132, s[22:23]
	s_mov_b32 m0, s53
	s_addc_u32 s7, s23, 0
	s_add_i32 s62, s21, 0x4000
	global_load_lds_dwordx4 v130, s[22:23]
	s_mov_b32 m0, s62
	s_add_i32 s63, s21, 0x6000
	global_load_lds_dwordx4 v132, s[6:7]
	s_mov_b32 m0, s63
	v_mov_b32_e32 v131, v157
	global_load_lds_dwordx4 v130, s[6:7]
	s_cmp_eq_u32 s5, 1
	v_lshl_add_u64 v[6:7], s[26:27], 0, v[156:157]
	v_lshl_add_u64 v[4:5], s[26:27], 0, v[128:129]
	v_lshl_add_u64 v[0:1], s[22:23], 0, v[132:133]
	s_cselect_b64 s[6:7], -1, 0
	s_cmp_lg_u32 s5, 1
	v_lshl_add_u64 v[2:3], s[22:23], 0, v[130:131]
	s_cbranch_scc1 .LBB0_175
	s_barrier

; #define PG8_PTRS(u, pa, pb) do { const size_t _ko = (u).ks >= 0 ? (size_t)(u).ks * (size_t)(K / KSPLIT) * 2 : 0; \
;         const char* _a = (const char*)g.A + (size_t)(u).pm * tstep + _ko; const char* _b = (const char*)g.Bt + (size_t)(u).pn * tstep + _ko; \
;         if ((u).pn >= g.nN_main) { pa = _b; pb = _a; } else { pa = _a; pb = _b; } } while (0)
; template <class EpiT, bool ALIGN_EPI>
; __device__ __forceinline__ void gemm_phase(LAS unsigned char* lds, const Gemm g, const StaticOrder& S, const EpiT& E, const int tid) {
;     ...
;     if (!S.next(0, cur)) return;
;     f32x4 acc[2][2][4][2];
; #pragma unroll
;     for (int a = 0; a < 2; ++a)
; #pragma unroll
;         for (int b = 0; b < 2; ++b)
; #pragma unroll
;             for (int m = 0; m < 4; ++m)
; #pragma unroll
;                 for (int n = 0; n < 2; ++n) acc[a][b][m][n] = (f32x4){0.f, 0.f, 0.f, 0.f};
;     bf16x8 At[4][2], B0[2][2], B1[2][2];
;     const char* cA; const char* cB; PG8_PTRS(cur, cA, cB);
.LBB0_340:
	s_andn2_b64 vcc, exec, s[50:51]
	s_cbranch_vccnz .LBB0_362
	v_readlane_b32 s0, v253, 16
	v_readlane_b32 s1, v253, 17
	s_andn2_b64 vcc, exec, s[0:1]
	v_readfirstlane_b32 s0, v166
	s_cbranch_vccnz .LBB0_362
	s_lshr_b32 s32, s2, 6
	s_and_b32 s32, s32, 3
	s_lshl_b32 s32, s32, 1
	s_cmp_eq_u32 s32, 0
	s_cbranch_scc1 .Lskew_done_win

; #define PG8_STAGE(bufoff, gbase, voff) do { _Pragma("unroll") for (int _i = 0; _i < 2; ++_i) \
;         __builtin_amdgcn_global_load_lds((const unsigned*)((const char*)(gbase) + (voff)[_i]), (LAS unsigned*)(lds + (bufoff) + ldsw + _i * 8192), 16, 0, 0); } while (0)
; #define PG8_WAIT_V(n) asm volatile("s_waitcnt vmcnt(" #n ")" ::: "memory")
; #define PG8_BAR __builtin_amdgcn_s_barrier()
; template <class EpiT, bool ALIGN_EPI>
; __device__ __forceinline__ void gemm_phase(LAS unsigned char* lds, const Gemm g, const StaticOrder& S, const EpiT& E, const int tid) {
;     const int wid = __builtin_amdgcn_readfirstlane(tid >> 6), lane = tid & 63, wr = wid >> 2, wc = wid & 3, fr = lane & 15, fq = lane >> 4;
;     const int K = g.K;
;     unsigned voffA[2], voffB[2];
; #pragma unroll
;     for (int i = 0; i < 2; ++i) { int R, C; stage_rc(tid * 16 + i * 8192, R, C); const int Rb = (R & ~31) + perm32(R & 31);
;         voffA[i] = (unsigned)(R * K + C) * 2u; voffB[i] = (unsigned)(Rb * K + C) * 2u; }
;     const size_t kstep = (size_t)(BK * 2);
;     const size_t hstep = (size_t)HALF * K * 2;
;     const size_t tstep = 2 * hstep;
;     const unsigned ldsw = (unsigned)wid * 1024u;
;     const int aoff = lds_byte(wr * 64 + fr, fq * 8), boff = lds_byte(wc * 32 + fr, fq * 8);
;     ...
;     Unit cur, nxt; int ui = 0;
;     if (!S.next(0, cur)) return;
;     f32x4 acc[2][2][4][2];
; #pragma unroll
;     for (int a = 0; a < 2; ++a)
; #pragma unroll
;         for (int b = 0; b < 2; ++b)
; #pragma unroll
;             for (int m = 0; m < 4; ++m)
; #pragma unroll
;                 for (int n = 0; n < 2; ++n) acc[a][b][m][n] = (f32x4){0.f, 0.f, 0.f, 0.f};
;     bf16x8 At[4][2], B0[2][2], B1[2][2];
;     const char* cA; const char* cB; PG8_PTRS(cur, cA, cB);
;     PG8_STAGE(PG8_SB(0, 0), cB, voffB); PG8_STAGE(PG8_SB(0, 1), cB + hstep, voffB); PG8_STAGE(PG8_SA(0, 0), cA, voffA); PG8_STAGE(PG8_SA(0, 1), cA + hstep, voffA);
;     if (wr == 1) PG8_BAR;
;     PG8_WAIT_V(2); PG8_BAR;
;     PG8_STAGE(PG8_SB(1, 0), cB + kstep, voffB); PG8_STAGE(PG8_SA(1, 0), cA + kstep, voffA); PG8_STAGE(PG8_SB(1, 1), cB + hstep + kstep, voffB);
;     PG8_WAIT_V(6); PG8_BAR;
.Lskew_done_win:
	s_waitcnt vmcnt(0)
	v_lshlrev_b32_e32 v3, 4, v166
	v_add_u32_e32 v1, 0x2000, v3
	v_ashrrev_i32_e32 v0, 31, v1
	v_lshrrev_b32_e32 v0, 22, v0
	v_add_u32_e32 v0, v1, v0
	v_ashrrev_i32_e32 v0, 10, v0
	v_mul_i32_i24_e32 v2, 0x400, v0
	v_sub_u32_e32 v1, v1, v2
	v_lshrrev_b32_e32 v2, 4, v1
	v_bitop3_b32 v2, v2, v1, 32 bitop3:0x6c
	v_readlane_b32 s4, v255, 17
	v_ashrrev_i32_e32 v1, 31, v2
	v_readlane_b32 s5, v255, 18
	v_lshrrev_b32_e32 v1, 26, v1
	s_ashr_i32 s5, s4, 31
	v_add_u32_e32 v4, v2, v1
	v_lshlrev_b32_e32 v5, 3, v0
	s_lshl_b64 s[4:5], s[4:5], 22
	v_ashrrev_i32_e32 v1, 6, v4
	v_and_b32_e32 v5, -16, v5
	s_add_u32 s1, s73, s4
	v_add_u32_e32 v5, v1, v5
	s_addc_u32 s4, s57, s5
	v_and_b32_e32 v6, 3, v1
	s_mov_b32 s5, 0x1fffe0
	v_lshrrev_b32_e32 v7, 2, v5
	v_lshlrev_b32_e32 v8, 1, v5
	v_and_b32_e32 v4, 0xc0, v4
	v_and_or_b32 v6, v5, s5, v6
	v_and_b32_e32 v7, 4, v7
	v_and_b32_e32 v8, 24, v8
	v_sub_u32_e32 v2, v2, v4
	v_or3_b32 v6, v6, v7, v8
	v_lshlrev_b32_e32 v7, 5, v0
	v_ashrrev_i16_sdwa v2, v252, sext(v2) dst_sel:DWORD dst_unused:UNUSED_PAD src0_sel:DWORD src1_sel:BYTE_0
	v_and_b32_e32 v7, 32, v7
	v_bfe_i32 v2, v2, 0, 16
	v_add_lshl_u32 v4, v7, v2, 1
	v_lshl_add_u32 v128, v6, 11, v4
	v_lshl_add_u32 v130, v5, 11, v4
	v_bfe_i32 v4, v166, 27, 1
	v_lshrrev_b32_e32 v4, 22, v4
	v_add_u32_e32 v4, v3, v4
	v_and_b32_e32 v4, 0xfffffc00, v4
	v_sub_u32_e32 v3, v3, v4
	v_lshrrev_b32_e32 v4, 4, v3
	v_bitop3_b32 v5, v4, v3, 32 bitop3:0x6c
	v_ashrrev_i32_e32 v4, 31, v166
	v_lshrrev_b32_e32 v4, 26, v4
	v_ashrrev_i32_e32 v3, 31, v5
	v_add_u32_e32 v4, v166, v4
	v_lshrrev_b32_e32 v3, 26, v3
	v_ashrrev_i32_e32 v4, 6, v4
	s_add_u32 s22, s1, 0xc00000
	v_add_u32_e32 v6, v5, v3
	v_lshlrev_b32_e32 v7, 3, v4
	s_addc_u32 s23, s4, 0
	s_ashr_i32 s4, s0, 6
	v_ashrrev_i32_e32 v3, 6, v6
	v_and_b32_e32 v7, -16, v7
	s_ashr_i32 s1, s0, 8
	s_lshl_b32 s24, s4, 10
	v_add_u32_e32 v7, v3, v7
	v_and_b32_e32 v8, 3, v3
	v_readlane_b32 s6, v254, 0
	v_and_or_b32 v8, v7, s5, v8
	v_readlane_b32 s7, v254, 1
	s_add_u32 s5, s94, s6
	v_lshrrev_b32_e32 v9, 2, v7
	v_lshlrev_b32_e32 v10, 1, v7
	v_and_b32_e32 v6, 0xc0, v6
	s_addc_u32 s8, s95, s7
	v_readlane_b32 s6, v253, 60
	v_and_b32_e32 v9, 4, v9
	v_and_b32_e32 v10, 24, v10
	v_sub_u32_e32 v5, v5, v6
	v_readlane_b32 s7, v253, 61
	s_add_u32 s9, s22, s6
	v_readlane_b32 s12, v254, 2
	v_or3_b32 v8, v8, v9, v10
	v_lshlrev_b32_e32 v9, 5, v4
	v_ashrrev_i16_sdwa v5, v252, sext(v5) dst_sel:DWORD dst_unused:UNUSED_PAD src0_sel:DWORD src1_sel:BYTE_0
	s_addc_u32 s10, s23, s7
	v_readlane_b32 s13, v254, 3
	v_and_b32_e32 v9, 32, v9
	v_bfe_i32 v5, v5, 0, 16
	s_and_b64 s[6:7], s[12:13], exec
	v_add_lshl_u32 v6, v9, v5, 1
	s_cselect_b32 s19, s8, s10
	s_cselect_b32 s18, s5, s9
	s_add_i32 s25, s24, 0
	v_lshl_add_u32 v156, v8, 11, v6
	s_add_i32 m0, s25, 0x10000
	v_lshl_add_u32 v132, v7, 11, v6
	global_load_lds_dwordx4 v156, s[18:19]
	s_add_i32 m0, s25, 0x12000
	s_add_u32 s6, s18, 0x40000
	global_load_lds_dwordx4 v128, s[18:19]
	s_addc_u32 s7, s19, 0
	s_add_i32 m0, s25, 0x14000
	s_nop 0
	global_load_lds_dwordx4 v156, s[6:7]
	s_add_i32 m0, s25, 0x16000
	s_nop 0
	global_load_lds_dwordx4 v128, s[6:7]
	s_and_b64 s[6:7], s[12:13], exec
	s_cselect_b32 s17, s10, s8
	s_cselect_b32 s16, s9, s5
	s_add_i32 s26, s25, 0x2000
	s_mov_b32 m0, s25
	s_add_u32 s6, s16, 0x40000
	global_load_lds_dwordx4 v132, s[16:17]
	s_mov_b32 m0, s26
	s_addc_u32 s7, s17, 0
	s_add_i32 s27, s25, 0x4000
	global_load_lds_dwordx4 v130, s[16:17]
	s_mov_b32 m0, s27
	s_add_i32 s28, s25, 0x6000
	global_load_lds_dwordx4 v132, s[6:7]
	s_mov_b32 m0, s28
	s_cmp_eq_u32 s1, 1
	global_load_lds_dwordx4 v130, s[6:7]
	s_cselect_b64 s[6:7], -1, 0
	s_cmp_lg_u32 s1, 1
	s_cbranch_scc1 .LBB0_344
	s_barrier
